# MLA attention tile loop: the per-interval loop-exit test uses a scalar compare against the interval count kept in an SGPR instead of a VALU compare through vcc; on attention zero-hoist stack
# baseline (speedup 1.0000x reference)
.LBB0_516:
	s_add_i32 s70, s68, s28
	s_lshl_b32 s30, s70, 1
	s_cmp_gt_u32 s69, 3
	s_cselect_b64 s[28:29], -1, 0
	v_cndmask_b32_e64 v0, 0, 1, s[28:29]
	v_or_b32_e32 v217, s30, v0
	v_mov_b32_e32 v0, v1
	v_mov_b32_e32 v2, v1
	v_mov_b32_e32 v3, v1
	v_mov_b32_e32 v4, v1
	v_mov_b32_e32 v5, v1
	v_mov_b32_e32 v6, v1
	v_mov_b32_e32 v7, v1
	v_mov_b32_e32 v8, v1
	v_mov_b32_e32 v9, v1
	v_mov_b32_e32 v10, v1
	v_mov_b32_e32 v11, v1
	v_mov_b32_e32 v12, v1
	v_mov_b32_e32 v13, v1
	v_mov_b32_e32 v14, v1
	v_mov_b32_e32 v15, v1
	v_mov_b32_e32 v16, v1
	v_mov_b32_e32 v17, v1
	v_mov_b32_e32 v18, v1
	v_mov_b32_e32 v19, v1
	v_mov_b32_e32 v20, v1
	v_mov_b32_e32 v21, v1
	v_mov_b32_e32 v22, v1
	v_mov_b32_e32 v23, v1
	v_mov_b32_e32 v24, v1
	v_mov_b32_e32 v25, v1
	v_mov_b32_e32 v26, v1
	v_mov_b32_e32 v27, v1
	v_mov_b32_e32 v28, v1
	v_mov_b32_e32 v29, v1
	v_mov_b32_e32 v30, v1
	v_mov_b32_e32 v31, v1
	v_mov_b32_e32 v32, v1
	v_mov_b32_e32 v33, v1
	v_mov_b32_e32 v34, v1
	v_mov_b32_e32 v35, v1
	v_mov_b32_e32 v36, v1
	v_mov_b32_e32 v37, v1
	v_mov_b32_e32 v38, v1
	v_mov_b32_e32 v39, v1
	v_mov_b32_e32 v40, v1
	v_mov_b32_e32 v41, v1
	s_cmp_lt_u32 s69, 4
	s_cselect_b64 s[22:23], -1, 0
	s_mov_b32 s71, 0
	v_readfirstlane_b32 s101, v217
	s_cmp_gt_u32 s69, 3
	s_cselect_b32 s100, 1, 0
	s_cselect_b32 s99, -1, 0
	s_mov_b32 s98, 0
	s_branch .LBB0_518
.LBB0_517:
	s_add_i32 s71, s71, 1
	s_cmp_eq_u32 s71, s101
	s_waitcnt lgkmcnt(0)
	s_barrier
	s_cbranch_scc1 .LBB0_538
